# Grid barrier: non-leader workgroups poll the top-level generation word directly (one hop), per-XCD generation word no longer written
# speedup vs baseline: 1.0066x; 1.0019x over previous
.LBB0_823:
	v_readlane_b32 s4, v253, 48
	s_lshl_b32 s20, s4, 6
	s_lshl_b64 s[4:5], s[20:21], 2
	v_readlane_b32 s6, v252, 4
	v_readlane_b32 s7, v252, 5
	s_add_u32 s4, s6, s4
	s_addc_u32 s5, s7, s5
	global_atomic_add v4, v211, v212, s[4:5] offset:1024 sc0
	v_cvt_f32_u32_e32 v1, v2
	v_sub_u32_e32 v5, 0, v2
	v_rcp_iflag_f32_e32 v1, v1
	s_nop 0
	v_mul_f32_e32 v1, 0x4f7ffffe, v1
	v_cvt_u32_f32_e32 v1, v1
	v_mul_lo_u32 v5, v5, v1
	v_mul_hi_u32 v5, v1, v5
	v_add_u32_e32 v1, v1, v5
	s_waitcnt vmcnt(0)
	v_mul_hi_u32 v1, v4, v1
	v_mul_lo_u32 v5, v1, v2
	v_sub_u32_e32 v5, v4, v5
	v_add_u32_e32 v6, 1, v1
	v_cmp_ge_u32_e32 vcc, v5, v2
	v_add_u32_e32 v4, 1, v4
	s_nop 0
	v_cndmask_b32_e32 v1, v1, v6, vcc
	v_sub_u32_e32 v6, v5, v2
	v_cndmask_b32_e32 v5, v5, v6, vcc
	v_add_u32_e32 v6, 1, v1
	v_cmp_ge_u32_e32 vcc, v5, v2
	s_nop 1
	v_cndmask_b32_e32 v1, v1, v6, vcc
	v_mul_lo_u32 v5, v2, v1
	v_add_u32_e32 v2, v5, v2
	v_cmp_ne_u32_e32 vcc, v4, v2
	s_and_saveexec_b64 s[6:7], vcc
	s_xor_b64 s[6:7], exec, s[6:7]
	s_cbranch_execz .LBB0_837
	s_waitcnt lgkmcnt(0)
	v_readlane_b32 s10, v253, 11
	v_readlane_b32 s11, v253, 12
	s_nop 4
	global_load_dword v0, v3, s[10:11] sc1
	s_waitcnt vmcnt(0)
	v_cmp_eq_u32_e32 vcc, v0, v1
	s_and_saveexec_b64 s[8:9], vcc
	s_cbranch_execz .LBB0_836
	s_mov_b32 s20, 1
	s_mov_b64 s[12:13], 0
	s_branch .LBB0_827

.LBB0_854:
	s_or_b64 exec, exec, s[6:7]
	s_waitcnt vmcnt(0)
	buffer_inv sc1
	s_waitcnt vmcnt(0)
